# v39 + loop layout: hot paths fall through to loop ends, tails out of line, single conditional back edge
# speedup vs baseline: 1.0001x; 1.0001x over previous
.LBB0_1610:
	s_waitcnt vmcnt(0)
	s_add_i32 s68, s68, 1
	s_mov_b64 s[4:5], 0x8000
	s_cmp_eq_u32 s67, s68
	v_lshl_add_u64 v[168:169], v[168:169], 0, s[4:5]
	s_barrier
	s_cbranch_scc0 .LBB0_1599
	s_branch .LBB0_1612
.Lyka_xtail:
	s_cmp_lg_u32 s59, s68
	s_cbranch_scc1 .LBB0_1610
	v_pk_add_f32 v[14:15], v[170:171], 0 op_sel_hi:[1,0]
	v_cvt_pk_bf16_f32 v124, v170, v172
	v_pk_add_f32 v[14:15], v[172:173], v[14:15]
	v_cvt_pk_bf16_f32 v125, v174, v176
	v_pk_add_f32 v[14:15], v[174:175], v[14:15]
	v_cvt_pk_bf16_f32 v126, v178, v180
	v_pk_add_f32 v[14:15], v[176:177], v[14:15]
	v_cvt_pk_bf16_f32 v127, v182, v184
	v_pk_add_f32 v[14:15], v[178:179], v[14:15]
	v_cvt_pk_bf16_f32 v128, v186, v188
	v_pk_add_f32 v[14:15], v[180:181], v[14:15]
	v_cvt_pk_bf16_f32 v129, v190, v192
	v_pk_add_f32 v[14:15], v[182:183], v[14:15]
	v_cvt_pk_bf16_f32 v130, v194, v196
	v_pk_add_f32 v[14:15], v[184:185], v[14:15]
	v_cvt_pk_bf16_f32 v131, v198, v200
	v_pk_add_f32 v[14:15], v[186:187], v[14:15]
	v_cvt_pk_bf16_f32 v132, v171, v173
	v_pk_add_f32 v[14:15], v[188:189], v[14:15]
	v_cvt_pk_bf16_f32 v133, v175, v177
	v_pk_add_f32 v[14:15], v[190:191], v[14:15]
	v_cvt_pk_bf16_f32 v134, v179, v181
	v_pk_add_f32 v[14:15], v[192:193], v[14:15]
	v_cvt_pk_bf16_f32 v135, v183, v185
	v_pk_add_f32 v[14:15], v[194:195], v[14:15]
	v_cvt_pk_bf16_f32 v136, v187, v189
	v_pk_add_f32 v[14:15], v[196:197], v[14:15]
	v_cvt_pk_bf16_f32 v137, v191, v193
	v_pk_add_f32 v[14:15], v[198:199], v[14:15]
	v_cvt_pk_bf16_f32 v138, v195, v197
	v_pk_add_f32 v[14:15], v[200:201], v[14:15]
	v_cvt_pk_bf16_f32 v139, v199, v201
	v_add_f32_e32 v0, v14, v15
	v_add_f32_e32 v210, v210, v0
	v_add_u32_e32 v14, s71, v209
	ds_read_b128 v[2:5], v14 offset:16384
	ds_read_b128 v[6:9], v14 offset:16896
	ds_read_b128 v[10:13], v14 offset:17408
	ds_read_b128 v[112:115], v14 offset:17920
	s_waitcnt lgkmcnt(0)
	v_mfma_f32_32x32x16_bf16 v[64:79], v[2:5], v[124:127], v[64:79]
	v_mfma_f32_32x32x16_bf16 v[48:63], v[6:9], v[124:127], v[48:63]
	v_mfma_f32_32x32x16_bf16 v[32:47], v[10:13], v[124:127], v[32:47]
	v_mfma_f32_32x32x16_bf16 v[16:31], v[112:115], v[124:127], v[16:31]
	ds_read_b128 v[2:5], v14 offset:20480
	ds_read_b128 v[6:9], v14 offset:20992
	ds_read_b128 v[10:13], v14 offset:21504
	ds_read_b128 v[112:115], v14 offset:22016
	s_waitcnt lgkmcnt(0)
	v_mfma_f32_32x32x16_bf16 v[64:79], v[2:5], v[128:131], v[64:79]
	v_mfma_f32_32x32x16_bf16 v[48:63], v[6:9], v[128:131], v[48:63]
	v_mfma_f32_32x32x16_bf16 v[32:47], v[10:13], v[128:131], v[32:47]
	v_mfma_f32_32x32x16_bf16 v[16:31], v[112:115], v[128:131], v[16:31]
	ds_read_b128 v[2:5], v14 offset:24576
	ds_read_b128 v[6:9], v14 offset:25088
	ds_read_b128 v[10:13], v14 offset:25600
	ds_read_b128 v[112:115], v14 offset:26112
	s_waitcnt lgkmcnt(0)
	v_mfma_f32_32x32x16_bf16 v[64:79], v[2:5], v[132:135], v[64:79]
	v_mfma_f32_32x32x16_bf16 v[48:63], v[6:9], v[132:135], v[48:63]
	v_mfma_f32_32x32x16_bf16 v[32:47], v[10:13], v[132:135], v[32:47]
	v_mfma_f32_32x32x16_bf16 v[16:31], v[112:115], v[132:135], v[16:31]
	ds_read_b128 v[2:5], v14 offset:28672
	ds_read_b128 v[6:9], v14 offset:29184
	ds_read_b128 v[10:13], v14 offset:29696
	ds_read_b128 v[112:115], v14 offset:30208
	s_waitcnt lgkmcnt(0)
	v_mfma_f32_32x32x16_bf16 v[64:79], v[2:5], v[136:139], v[64:79]
	v_mfma_f32_32x32x16_bf16 v[48:63], v[6:9], v[136:139], v[48:63]
	v_mfma_f32_32x32x16_bf16 v[32:47], v[10:13], v[136:139], v[32:47]
	v_mfma_f32_32x32x16_bf16 v[16:31], v[112:115], v[136:139], v[16:31]
	s_branch .LBB0_1610

.Lyka_ynext:
	s_add_i32 s68, s68, 1
	s_mov_b64 s[4:5], 0x8000
	s_cmp_eq_u32 s67, s68
	v_lshl_add_u64 v[168:169], v[168:169], 0, s[4:5]
	s_cbranch_scc0 .Lyka_ytop
	s_branch .LBB0_1612

.Lyka_yidle:
	s_waitcnt vmcnt(0)
	s_barrier
	s_branch .Lyka_ynext

.LBB0_2163:
	s_waitcnt vmcnt(0)
	s_add_i32 s78, s78, 1
	s_mov_b64 s[4:5], 0x8000
	s_cmp_eq_u32 s69, s78
	v_lshl_add_u64 v[170:171], v[170:171], 0, s[4:5]
	s_barrier
	s_cbranch_scc0 .LBB0_2152
	s_branch .LBB0_2165
.Lykb_xtail:
	s_cmp_lg_u32 s66, s78
	s_cbranch_scc1 .LBB0_2163
	v_pk_add_f32 v[14:15], v[168:169], 0 op_sel_hi:[1,0]
	v_cvt_pk_bf16_f32 v124, v168, v172
	v_pk_add_f32 v[14:15], v[172:173], v[14:15]
	v_cvt_pk_bf16_f32 v125, v174, v176
	v_pk_add_f32 v[14:15], v[174:175], v[14:15]
	v_cvt_pk_bf16_f32 v126, v178, v180
	v_pk_add_f32 v[14:15], v[176:177], v[14:15]
	v_cvt_pk_bf16_f32 v127, v182, v184
	v_pk_add_f32 v[14:15], v[178:179], v[14:15]
	v_cvt_pk_bf16_f32 v128, v186, v188
	v_pk_add_f32 v[14:15], v[180:181], v[14:15]
	v_cvt_pk_bf16_f32 v129, v190, v192
	v_pk_add_f32 v[14:15], v[182:183], v[14:15]
	v_cvt_pk_bf16_f32 v130, v194, v196
	v_pk_add_f32 v[14:15], v[184:185], v[14:15]
	v_cvt_pk_bf16_f32 v131, v198, v200
	v_pk_add_f32 v[14:15], v[186:187], v[14:15]
	v_cvt_pk_bf16_f32 v132, v169, v173
	v_pk_add_f32 v[14:15], v[188:189], v[14:15]
	v_cvt_pk_bf16_f32 v133, v175, v177
	v_pk_add_f32 v[14:15], v[190:191], v[14:15]
	v_cvt_pk_bf16_f32 v134, v179, v181
	v_pk_add_f32 v[14:15], v[192:193], v[14:15]
	v_cvt_pk_bf16_f32 v135, v183, v185
	v_pk_add_f32 v[14:15], v[194:195], v[14:15]
	v_cvt_pk_bf16_f32 v136, v187, v189
	v_pk_add_f32 v[14:15], v[196:197], v[14:15]
	v_cvt_pk_bf16_f32 v137, v191, v193
	v_pk_add_f32 v[14:15], v[198:199], v[14:15]
	v_cvt_pk_bf16_f32 v138, v195, v197
	v_pk_add_f32 v[14:15], v[200:201], v[14:15]
	v_cvt_pk_bf16_f32 v139, v199, v201
	v_add_f32_e32 v0, v14, v15
	v_add_f32_e32 v210, v210, v0
	v_add_u32_e32 v14, s80, v209
	ds_read_b128 v[2:5], v14 offset:16384
	ds_read_b128 v[6:9], v14 offset:16896
	ds_read_b128 v[10:13], v14 offset:17408
	ds_read_b128 v[112:115], v14 offset:17920
	s_waitcnt lgkmcnt(0)
	v_mfma_f32_32x32x16_bf16 v[64:79], v[2:5], v[124:127], v[64:79]
	v_mfma_f32_32x32x16_bf16 v[48:63], v[6:9], v[124:127], v[48:63]
	v_mfma_f32_32x32x16_bf16 v[32:47], v[10:13], v[124:127], v[32:47]
	v_mfma_f32_32x32x16_bf16 v[16:31], v[112:115], v[124:127], v[16:31]
	ds_read_b128 v[2:5], v14 offset:20480
	ds_read_b128 v[6:9], v14 offset:20992
	ds_read_b128 v[10:13], v14 offset:21504
	ds_read_b128 v[112:115], v14 offset:22016
	s_waitcnt lgkmcnt(0)
	v_mfma_f32_32x32x16_bf16 v[64:79], v[2:5], v[128:131], v[64:79]
	v_mfma_f32_32x32x16_bf16 v[48:63], v[6:9], v[128:131], v[48:63]
	v_mfma_f32_32x32x16_bf16 v[32:47], v[10:13], v[128:131], v[32:47]
	v_mfma_f32_32x32x16_bf16 v[16:31], v[112:115], v[128:131], v[16:31]
	ds_read_b128 v[2:5], v14 offset:24576
	ds_read_b128 v[6:9], v14 offset:25088
	ds_read_b128 v[10:13], v14 offset:25600
	ds_read_b128 v[112:115], v14 offset:26112
	s_waitcnt lgkmcnt(0)
	v_mfma_f32_32x32x16_bf16 v[64:79], v[2:5], v[132:135], v[64:79]
	v_mfma_f32_32x32x16_bf16 v[48:63], v[6:9], v[132:135], v[48:63]
	v_mfma_f32_32x32x16_bf16 v[32:47], v[10:13], v[132:135], v[32:47]
	v_mfma_f32_32x32x16_bf16 v[16:31], v[112:115], v[132:135], v[16:31]
	ds_read_b128 v[2:5], v14 offset:28672
	ds_read_b128 v[6:9], v14 offset:29184
	ds_read_b128 v[10:13], v14 offset:29696
	ds_read_b128 v[112:115], v14 offset:30208
	s_waitcnt lgkmcnt(0)
	v_mfma_f32_32x32x16_bf16 v[64:79], v[2:5], v[136:139], v[64:79]
	v_mfma_f32_32x32x16_bf16 v[48:63], v[6:9], v[136:139], v[48:63]
	v_mfma_f32_32x32x16_bf16 v[32:47], v[10:13], v[136:139], v[32:47]
	v_mfma_f32_32x32x16_bf16 v[16:31], v[112:115], v[136:139], v[16:31]
	s_branch .LBB0_2163

.Lykb_ynext:
	s_add_i32 s78, s78, 1
	s_mov_b64 s[4:5], 0x8000
	s_cmp_eq_u32 s69, s78
	v_lshl_add_u64 v[170:171], v[170:171], 0, s[4:5]
	s_cbranch_scc0 .Lykb_ytop
	s_branch .LBB0_2165
